# scan fixup phase rewritten on the f32 matrix cores (v_mfma_f32_32x32x2_f32, S and YM rows straight to operands, no broadcast loads / LDS), on top of v71
# speedup vs baseline: 1.0292x; 1.0292x over previous
.LBB0_731:
	s_or_b64 exec, exec, s[2:3]
	s_waitcnt lgkmcnt(0)
	s_barrier
	s_getreg_b32 s0, hwreg(HW_REG_HW_ID, 0, 6)
	s_and_b32 s0, s0, 63
	s_lshl_b32 s0, s0, 2
	s_add_i32 s0, s0, 0x22ef0
	v_mov_b32_e32 v0, s0
	ds_read_b32 v0, v0
	v_mbcnt_lo_u32_b32 v1, -1, v177
	v_mbcnt_hi_u32_b32 v1, -1, v1
	v_readlane_b32 s1, v254, 27
	v_readlane_b32 s2, v254, 28
	v_readlane_b32 s3, v253, 18
	v_readlane_b32 s4, v253, 19
	v_and_b32_e32 v2, 31, v1
	v_lshrrev_b32_e32 v3, 5, v1
	v_lshlrev_b32_e32 v4, 7, v3
	v_lshl_add_u32 v220, v2, 12, v4
	v_lshl_add_u32 v221, v2, 8, v4
	v_lshlrev_b32_e32 v4, 3, v3
	v_lshl_add_u32 v222, v2, 11, v4
	s_waitcnt lgkmcnt(0)
	v_readfirstlane_b32 s0, v0
	s_add_i32 s1, s1, s2
	s_add_i32 s4, s4, s2
	s_lshl_b32 s5, s0, 6
	s_add_i32 s1, s1, s5
	s_add_i32 s4, s4, s5
	s_lshl_b32 s1, s1, 12
	s_lshl_b32 s2, s3, 2
	s_add_u32 s1, s1, s2
	s_add_u32 s1, s1, 0x6500000
	s_add_u32 s8, s66, s1
	s_addc_u32 s9, s67, 0
	s_add_u32 s10, s8, 0x20000
	s_addc_u32 s11, s9, 0
	s_lshl_b32 s4, s4, 11
	s_lshl_b32 s2, s3, 1
	s_add_u32 s4, s4, s2
	s_add_u32 s4, s4, 0x15000000
	s_add_u32 s12, s66, s4
	s_addc_u32 s13, s67, 0
	s_add_u32 s2, s12, 0x10000
	s_addc_u32 s3, s13, 0
	v_readlane_b32 s4, v253, 16
	v_readlane_b32 s5, v253, 17
	s_nop 1
	s_add_u32 s4, s4, 0xec00000
	s_addc_u32 s5, s5, 0
	s_add_u32 s6, s4, 0x2000
	s_addc_u32 s7, s5, 0
	global_load_dwordx4 v[0:3], v221, s[4:5] offset:0
	global_load_dwordx4 v[4:7], v221, s[4:5] offset:16
	global_load_dwordx4 v[8:11], v221, s[4:5] offset:32
	global_load_dwordx4 v[12:15], v221, s[4:5] offset:48
	global_load_dwordx4 v[16:19], v221, s[4:5] offset:64
	global_load_dwordx4 v[20:23], v221, s[4:5] offset:80
	global_load_dwordx4 v[24:27], v221, s[4:5] offset:96
	global_load_dwordx4 v[28:31], v221, s[4:5] offset:112
	global_load_dwordx4 v[32:35], v221, s[6:7] offset:0
	global_load_dwordx4 v[36:39], v221, s[6:7] offset:16
	global_load_dwordx4 v[40:43], v221, s[6:7] offset:32
	global_load_dwordx4 v[44:47], v221, s[6:7] offset:48
	global_load_dwordx4 v[48:51], v221, s[6:7] offset:64
	global_load_dwordx4 v[52:55], v221, s[6:7] offset:80
	global_load_dwordx4 v[56:59], v221, s[6:7] offset:96
	global_load_dwordx4 v[60:63], v221, s[6:7] offset:112
	global_load_dwordx4 v[64:67], v220, s[8:9] offset:0
	global_load_dwordx4 v[68:71], v220, s[8:9] offset:16
	global_load_dwordx4 v[72:75], v220, s[8:9] offset:32
	global_load_dwordx4 v[76:79], v220, s[8:9] offset:48
	global_load_dwordx4 v[80:83], v220, s[8:9] offset:64
	global_load_dwordx4 v[84:87], v220, s[8:9] offset:80
	global_load_dwordx4 v[88:91], v220, s[8:9] offset:96
	global_load_dwordx4 v[92:95], v220, s[8:9] offset:112
	global_load_dwordx2 v[204:205], v222, s[12:13] offset:0
	global_load_dwordx2 v[206:207], v222, s[12:13] offset:16
	global_load_dwordx2 v[208:209], v222, s[12:13] offset:32
	global_load_dwordx2 v[210:211], v222, s[12:13] offset:48
	global_load_dwordx2 v[212:213], v222, s[12:13] offset:64
	global_load_dwordx2 v[214:215], v222, s[12:13] offset:80
	global_load_dwordx2 v[216:217], v222, s[12:13] offset:96
	global_load_dwordx2 v[218:219], v222, s[12:13] offset:112
	global_load_dwordx4 v[96:99], v220, s[10:11] offset:0
	global_load_dwordx4 v[100:103], v220, s[10:11] offset:16
	global_load_dwordx4 v[104:107], v220, s[10:11] offset:32
	global_load_dwordx4 v[108:111], v220, s[10:11] offset:48
	global_load_dwordx4 v[112:115], v220, s[10:11] offset:64
	global_load_dwordx4 v[116:119], v220, s[10:11] offset:80
	global_load_dwordx4 v[120:123], v220, s[10:11] offset:96
	global_load_dwordx4 v[124:127], v220, s[10:11] offset:112
	s_waitcnt vmcnt(16)
	v_mfma_f32_32x32x2_f32 v[128:143], v0, v64, 0
	v_mfma_f32_32x32x2_f32 v[144:159], v32, v64, 0
	v_mfma_f32_32x32x2_f32 v[128:143], v1, v65, v[128:143]
	v_mfma_f32_32x32x2_f32 v[144:159], v33, v65, v[144:159]
	v_mfma_f32_32x32x2_f32 v[128:143], v2, v66, v[128:143]
	v_mfma_f32_32x32x2_f32 v[144:159], v34, v66, v[144:159]
	v_mfma_f32_32x32x2_f32 v[128:143], v3, v67, v[128:143]
	v_mfma_f32_32x32x2_f32 v[144:159], v35, v67, v[144:159]
	v_mfma_f32_32x32x2_f32 v[128:143], v4, v68, v[128:143]
	v_mfma_f32_32x32x2_f32 v[144:159], v36, v68, v[144:159]
	v_mfma_f32_32x32x2_f32 v[128:143], v5, v69, v[128:143]
	v_mfma_f32_32x32x2_f32 v[144:159], v37, v69, v[144:159]
	v_mfma_f32_32x32x2_f32 v[128:143], v6, v70, v[128:143]
	v_mfma_f32_32x32x2_f32 v[144:159], v38, v70, v[144:159]
	v_mfma_f32_32x32x2_f32 v[128:143], v7, v71, v[128:143]
	v_mfma_f32_32x32x2_f32 v[144:159], v39, v71, v[144:159]
	v_mfma_f32_32x32x2_f32 v[128:143], v8, v72, v[128:143]
	v_mfma_f32_32x32x2_f32 v[144:159], v40, v72, v[144:159]
	v_mfma_f32_32x32x2_f32 v[128:143], v9, v73, v[128:143]
	v_mfma_f32_32x32x2_f32 v[144:159], v41, v73, v[144:159]
	v_mfma_f32_32x32x2_f32 v[128:143], v10, v74, v[128:143]
	v_mfma_f32_32x32x2_f32 v[144:159], v42, v74, v[144:159]
	v_mfma_f32_32x32x2_f32 v[128:143], v11, v75, v[128:143]
	v_mfma_f32_32x32x2_f32 v[144:159], v43, v75, v[144:159]
	v_mfma_f32_32x32x2_f32 v[128:143], v12, v76, v[128:143]
	v_mfma_f32_32x32x2_f32 v[144:159], v44, v76, v[144:159]
	v_mfma_f32_32x32x2_f32 v[128:143], v13, v77, v[128:143]
	v_mfma_f32_32x32x2_f32 v[144:159], v45, v77, v[144:159]
	v_mfma_f32_32x32x2_f32 v[128:143], v14, v78, v[128:143]
	v_mfma_f32_32x32x2_f32 v[144:159], v46, v78, v[144:159]
	v_mfma_f32_32x32x2_f32 v[128:143], v15, v79, v[128:143]
	v_mfma_f32_32x32x2_f32 v[144:159], v47, v79, v[144:159]
	v_mfma_f32_32x32x2_f32 v[128:143], v16, v80, v[128:143]
	v_mfma_f32_32x32x2_f32 v[144:159], v48, v80, v[144:159]
	v_mfma_f32_32x32x2_f32 v[128:143], v17, v81, v[128:143]
	v_mfma_f32_32x32x2_f32 v[144:159], v49, v81, v[144:159]
	v_mfma_f32_32x32x2_f32 v[128:143], v18, v82, v[128:143]
	v_mfma_f32_32x32x2_f32 v[144:159], v50, v82, v[144:159]
	v_mfma_f32_32x32x2_f32 v[128:143], v19, v83, v[128:143]
	v_mfma_f32_32x32x2_f32 v[144:159], v51, v83, v[144:159]
	v_mfma_f32_32x32x2_f32 v[128:143], v20, v84, v[128:143]
	v_mfma_f32_32x32x2_f32 v[144:159], v52, v84, v[144:159]
	v_mfma_f32_32x32x2_f32 v[128:143], v21, v85, v[128:143]
	v_mfma_f32_32x32x2_f32 v[144:159], v53, v85, v[144:159]
	v_mfma_f32_32x32x2_f32 v[128:143], v22, v86, v[128:143]
	v_mfma_f32_32x32x2_f32 v[144:159], v54, v86, v[144:159]
	v_mfma_f32_32x32x2_f32 v[128:143], v23, v87, v[128:143]
	v_mfma_f32_32x32x2_f32 v[144:159], v55, v87, v[144:159]
	v_mfma_f32_32x32x2_f32 v[128:143], v24, v88, v[128:143]
	v_mfma_f32_32x32x2_f32 v[144:159], v56, v88, v[144:159]
	v_mfma_f32_32x32x2_f32 v[128:143], v25, v89, v[128:143]
	v_mfma_f32_32x32x2_f32 v[144:159], v57, v89, v[144:159]
	v_mfma_f32_32x32x2_f32 v[128:143], v26, v90, v[128:143]
	v_mfma_f32_32x32x2_f32 v[144:159], v58, v90, v[144:159]
	v_mfma_f32_32x32x2_f32 v[128:143], v27, v91, v[128:143]
	v_mfma_f32_32x32x2_f32 v[144:159], v59, v91, v[144:159]
	v_mfma_f32_32x32x2_f32 v[128:143], v28, v92, v[128:143]
	v_mfma_f32_32x32x2_f32 v[144:159], v60, v92, v[144:159]
	v_mfma_f32_32x32x2_f32 v[128:143], v29, v93, v[128:143]
	v_mfma_f32_32x32x2_f32 v[144:159], v61, v93, v[144:159]
	v_mfma_f32_32x32x2_f32 v[128:143], v30, v94, v[128:143]
	v_mfma_f32_32x32x2_f32 v[144:159], v62, v94, v[144:159]
	v_mfma_f32_32x32x2_f32 v[128:143], v31, v95, v[128:143]
	v_mfma_f32_32x32x2_f32 v[144:159], v63, v95, v[144:159]
	global_load_dwordx2 v[64:65], v222, s[2:3] offset:0
	global_load_dwordx2 v[66:67], v222, s[2:3] offset:16
	global_load_dwordx2 v[68:69], v222, s[2:3] offset:32
	global_load_dwordx2 v[70:71], v222, s[2:3] offset:48
	global_load_dwordx2 v[72:73], v222, s[2:3] offset:64
	global_load_dwordx2 v[74:75], v222, s[2:3] offset:80
	global_load_dwordx2 v[76:77], v222, s[2:3] offset:96
	global_load_dwordx2 v[78:79], v222, s[2:3] offset:112
	s_waitcnt vmcnt(8)
	v_mfma_f32_32x32x2_f32 v[160:175], v0, v96, 0
	v_mfma_f32_32x32x2_f32 v[188:203], v32, v96, 0
	v_mfma_f32_32x32x2_f32 v[160:175], v1, v97, v[160:175]
	v_mfma_f32_32x32x2_f32 v[188:203], v33, v97, v[188:203]
	v_mfma_f32_32x32x2_f32 v[160:175], v2, v98, v[160:175]
	v_mfma_f32_32x32x2_f32 v[188:203], v34, v98, v[188:203]
	v_mfma_f32_32x32x2_f32 v[160:175], v3, v99, v[160:175]
	v_mfma_f32_32x32x2_f32 v[188:203], v35, v99, v[188:203]
	v_mfma_f32_32x32x2_f32 v[160:175], v4, v100, v[160:175]
	v_mfma_f32_32x32x2_f32 v[188:203], v36, v100, v[188:203]
	v_mfma_f32_32x32x2_f32 v[160:175], v5, v101, v[160:175]
	v_mfma_f32_32x32x2_f32 v[188:203], v37, v101, v[188:203]
	v_mfma_f32_32x32x2_f32 v[160:175], v6, v102, v[160:175]
	v_mfma_f32_32x32x2_f32 v[188:203], v38, v102, v[188:203]
	v_mfma_f32_32x32x2_f32 v[160:175], v7, v103, v[160:175]
	v_mfma_f32_32x32x2_f32 v[188:203], v39, v103, v[188:203]
	v_mfma_f32_32x32x2_f32 v[160:175], v8, v104, v[160:175]
	v_mfma_f32_32x32x2_f32 v[188:203], v40, v104, v[188:203]
	v_mfma_f32_32x32x2_f32 v[160:175], v9, v105, v[160:175]
	v_mfma_f32_32x32x2_f32 v[188:203], v41, v105, v[188:203]
	v_mfma_f32_32x32x2_f32 v[160:175], v10, v106, v[160:175]
	v_mfma_f32_32x32x2_f32 v[188:203], v42, v106, v[188:203]
	v_mfma_f32_32x32x2_f32 v[160:175], v11, v107, v[160:175]
	v_mfma_f32_32x32x2_f32 v[188:203], v43, v107, v[188:203]
	v_mfma_f32_32x32x2_f32 v[160:175], v12, v108, v[160:175]
	v_mfma_f32_32x32x2_f32 v[188:203], v44, v108, v[188:203]
	v_mfma_f32_32x32x2_f32 v[160:175], v13, v109, v[160:175]
	v_mfma_f32_32x32x2_f32 v[188:203], v45, v109, v[188:203]
	v_mfma_f32_32x32x2_f32 v[160:175], v14, v110, v[160:175]
	v_mfma_f32_32x32x2_f32 v[188:203], v46, v110, v[188:203]
	v_mfma_f32_32x32x2_f32 v[160:175], v15, v111, v[160:175]
	v_mfma_f32_32x32x2_f32 v[188:203], v47, v111, v[188:203]
	v_mfma_f32_32x32x2_f32 v[160:175], v16, v112, v[160:175]
	v_mfma_f32_32x32x2_f32 v[188:203], v48, v112, v[188:203]
	v_mfma_f32_32x32x2_f32 v[160:175], v17, v113, v[160:175]
	v_mfma_f32_32x32x2_f32 v[188:203], v49, v113, v[188:203]
	v_mfma_f32_32x32x2_f32 v[160:175], v18, v114, v[160:175]
	v_mfma_f32_32x32x2_f32 v[188:203], v50, v114, v[188:203]
	v_mfma_f32_32x32x2_f32 v[160:175], v19, v115, v[160:175]
	v_mfma_f32_32x32x2_f32 v[188:203], v51, v115, v[188:203]
	v_mfma_f32_32x32x2_f32 v[160:175], v20, v116, v[160:175]
	v_mfma_f32_32x32x2_f32 v[188:203], v52, v116, v[188:203]
	v_mfma_f32_32x32x2_f32 v[160:175], v21, v117, v[160:175]
	v_mfma_f32_32x32x2_f32 v[188:203], v53, v117, v[188:203]
	v_mfma_f32_32x32x2_f32 v[160:175], v22, v118, v[160:175]
	v_mfma_f32_32x32x2_f32 v[188:203], v54, v118, v[188:203]
	v_mfma_f32_32x32x2_f32 v[160:175], v23, v119, v[160:175]
	v_mfma_f32_32x32x2_f32 v[188:203], v55, v119, v[188:203]
	v_mfma_f32_32x32x2_f32 v[160:175], v24, v120, v[160:175]
	v_mfma_f32_32x32x2_f32 v[188:203], v56, v120, v[188:203]
	v_mfma_f32_32x32x2_f32 v[160:175], v25, v121, v[160:175]
	v_mfma_f32_32x32x2_f32 v[188:203], v57, v121, v[188:203]
	v_mfma_f32_32x32x2_f32 v[160:175], v26, v122, v[160:175]
	v_mfma_f32_32x32x2_f32 v[188:203], v58, v122, v[188:203]
	v_mfma_f32_32x32x2_f32 v[160:175], v27, v123, v[160:175]
	v_mfma_f32_32x32x2_f32 v[188:203], v59, v123, v[188:203]
	v_mfma_f32_32x32x2_f32 v[160:175], v28, v124, v[160:175]
	v_mfma_f32_32x32x2_f32 v[188:203], v60, v124, v[188:203]
	v_mfma_f32_32x32x2_f32 v[160:175], v29, v125, v[160:175]
	v_mfma_f32_32x32x2_f32 v[188:203], v61, v125, v[188:203]
	v_mfma_f32_32x32x2_f32 v[160:175], v30, v126, v[160:175]
	v_mfma_f32_32x32x2_f32 v[188:203], v62, v126, v[188:203]
	v_mfma_f32_32x32x2_f32 v[160:175], v31, v127, v[160:175]
	v_mfma_f32_32x32x2_f32 v[188:203], v63, v127, v[188:203]
	s_nop 15
	s_nop 7
	v_lshlrev_b32_e32 v223, 16, v204
	v_and_b32_e32 v204, 0xffff0000, v204
	v_add_f32_e32 v223, v223, v128
	v_add_f32_e32 v204, v204, v129
	v_cvt_pk_bf16_f32 v204, v223, v204
	v_lshlrev_b32_e32 v223, 16, v205
	v_and_b32_e32 v205, 0xffff0000, v205
	v_add_f32_e32 v223, v223, v130
	v_add_f32_e32 v205, v205, v131
	v_cvt_pk_bf16_f32 v205, v223, v205
	global_store_dwordx2 v222, v[204:205], s[12:13] offset:0
	v_lshlrev_b32_e32 v223, 16, v206
	v_and_b32_e32 v206, 0xffff0000, v206
	v_add_f32_e32 v223, v223, v132
	v_add_f32_e32 v206, v206, v133
	v_cvt_pk_bf16_f32 v206, v223, v206
	v_lshlrev_b32_e32 v223, 16, v207
	v_and_b32_e32 v207, 0xffff0000, v207
	v_add_f32_e32 v223, v223, v134
	v_add_f32_e32 v207, v207, v135
	v_cvt_pk_bf16_f32 v207, v223, v207
	global_store_dwordx2 v222, v[206:207], s[12:13] offset:16
	v_lshlrev_b32_e32 v223, 16, v208
	v_and_b32_e32 v208, 0xffff0000, v208
	v_add_f32_e32 v223, v223, v136
	v_add_f32_e32 v208, v208, v137
	v_cvt_pk_bf16_f32 v208, v223, v208
	v_lshlrev_b32_e32 v223, 16, v209
	v_and_b32_e32 v209, 0xffff0000, v209
	v_add_f32_e32 v223, v223, v138
	v_add_f32_e32 v209, v209, v139
	v_cvt_pk_bf16_f32 v209, v223, v209
	global_store_dwordx2 v222, v[208:209], s[12:13] offset:32
	v_lshlrev_b32_e32 v223, 16, v210
	v_and_b32_e32 v210, 0xffff0000, v210
	v_add_f32_e32 v223, v223, v140
	v_add_f32_e32 v210, v210, v141
	v_cvt_pk_bf16_f32 v210, v223, v210
	v_lshlrev_b32_e32 v223, 16, v211
	v_and_b32_e32 v211, 0xffff0000, v211
	v_add_f32_e32 v223, v223, v142
	v_add_f32_e32 v211, v211, v143
	v_cvt_pk_bf16_f32 v211, v223, v211
	global_store_dwordx2 v222, v[210:211], s[12:13] offset:48
	v_lshlrev_b32_e32 v223, 16, v212
	v_and_b32_e32 v212, 0xffff0000, v212
	v_add_f32_e32 v223, v223, v144
	v_add_f32_e32 v212, v212, v145
	v_cvt_pk_bf16_f32 v212, v223, v212
	v_lshlrev_b32_e32 v223, 16, v213
	v_and_b32_e32 v213, 0xffff0000, v213
	v_add_f32_e32 v223, v223, v146
	v_add_f32_e32 v213, v213, v147
	v_cvt_pk_bf16_f32 v213, v223, v213
	global_store_dwordx2 v222, v[212:213], s[12:13] offset:64
	v_lshlrev_b32_e32 v223, 16, v214
	v_and_b32_e32 v214, 0xffff0000, v214
	v_add_f32_e32 v223, v223, v148
	v_add_f32_e32 v214, v214, v149
	v_cvt_pk_bf16_f32 v214, v223, v214
	v_lshlrev_b32_e32 v223, 16, v215
	v_and_b32_e32 v215, 0xffff0000, v215
	v_add_f32_e32 v223, v223, v150
	v_add_f32_e32 v215, v215, v151
	v_cvt_pk_bf16_f32 v215, v223, v215
	global_store_dwordx2 v222, v[214:215], s[12:13] offset:80
	v_lshlrev_b32_e32 v223, 16, v216
	v_and_b32_e32 v216, 0xffff0000, v216
	v_add_f32_e32 v223, v223, v152
	v_add_f32_e32 v216, v216, v153
	v_cvt_pk_bf16_f32 v216, v223, v216
	v_lshlrev_b32_e32 v223, 16, v217
	v_and_b32_e32 v217, 0xffff0000, v217
	v_add_f32_e32 v223, v223, v154
	v_add_f32_e32 v217, v217, v155
	v_cvt_pk_bf16_f32 v217, v223, v217
	global_store_dwordx2 v222, v[216:217], s[12:13] offset:96
	v_lshlrev_b32_e32 v223, 16, v218
	v_and_b32_e32 v218, 0xffff0000, v218
	v_add_f32_e32 v223, v223, v156
	v_add_f32_e32 v218, v218, v157
	v_cvt_pk_bf16_f32 v218, v223, v218
	v_lshlrev_b32_e32 v223, 16, v219
	v_and_b32_e32 v219, 0xffff0000, v219
	v_add_f32_e32 v223, v223, v158
	v_add_f32_e32 v219, v219, v159
	v_cvt_pk_bf16_f32 v219, v223, v219
	global_store_dwordx2 v222, v[218:219], s[12:13] offset:112
	s_waitcnt vmcnt(0)
	v_lshlrev_b32_e32 v223, 16, v64
	v_and_b32_e32 v64, 0xffff0000, v64
	v_add_f32_e32 v223, v223, v160
	v_add_f32_e32 v64, v64, v161
	v_cvt_pk_bf16_f32 v64, v223, v64
	v_lshlrev_b32_e32 v223, 16, v65
	v_and_b32_e32 v65, 0xffff0000, v65
	v_add_f32_e32 v223, v223, v162
	v_add_f32_e32 v65, v65, v163
	v_cvt_pk_bf16_f32 v65, v223, v65
	global_store_dwordx2 v222, v[64:65], s[2:3] offset:0
	v_lshlrev_b32_e32 v223, 16, v66
	v_and_b32_e32 v66, 0xffff0000, v66
	v_add_f32_e32 v223, v223, v164
	v_add_f32_e32 v66, v66, v165
	v_cvt_pk_bf16_f32 v66, v223, v66
	v_lshlrev_b32_e32 v223, 16, v67
	v_and_b32_e32 v67, 0xffff0000, v67
	v_add_f32_e32 v223, v223, v166
	v_add_f32_e32 v67, v67, v167
	v_cvt_pk_bf16_f32 v67, v223, v67
	global_store_dwordx2 v222, v[66:67], s[2:3] offset:16
	v_lshlrev_b32_e32 v223, 16, v68
	v_and_b32_e32 v68, 0xffff0000, v68
	v_add_f32_e32 v223, v223, v168
	v_add_f32_e32 v68, v68, v169
	v_cvt_pk_bf16_f32 v68, v223, v68
	v_lshlrev_b32_e32 v223, 16, v69
	v_and_b32_e32 v69, 0xffff0000, v69
	v_add_f32_e32 v223, v223, v170
	v_add_f32_e32 v69, v69, v171
	v_cvt_pk_bf16_f32 v69, v223, v69
	global_store_dwordx2 v222, v[68:69], s[2:3] offset:32
	v_lshlrev_b32_e32 v223, 16, v70
	v_and_b32_e32 v70, 0xffff0000, v70
	v_add_f32_e32 v223, v223, v172
	v_add_f32_e32 v70, v70, v173
	v_cvt_pk_bf16_f32 v70, v223, v70
	v_lshlrev_b32_e32 v223, 16, v71
	v_and_b32_e32 v71, 0xffff0000, v71
	v_add_f32_e32 v223, v223, v174
	v_add_f32_e32 v71, v71, v175
	v_cvt_pk_bf16_f32 v71, v223, v71
	global_store_dwordx2 v222, v[70:71], s[2:3] offset:48
	v_lshlrev_b32_e32 v223, 16, v72
	v_and_b32_e32 v72, 0xffff0000, v72
	v_add_f32_e32 v223, v223, v188
	v_add_f32_e32 v72, v72, v189
	v_cvt_pk_bf16_f32 v72, v223, v72
	v_lshlrev_b32_e32 v223, 16, v73
	v_and_b32_e32 v73, 0xffff0000, v73
	v_add_f32_e32 v223, v223, v190
	v_add_f32_e32 v73, v73, v191
	v_cvt_pk_bf16_f32 v73, v223, v73
	global_store_dwordx2 v222, v[72:73], s[2:3] offset:64
	v_lshlrev_b32_e32 v223, 16, v74
	v_and_b32_e32 v74, 0xffff0000, v74
	v_add_f32_e32 v223, v223, v192
	v_add_f32_e32 v74, v74, v193
	v_cvt_pk_bf16_f32 v74, v223, v74
	v_lshlrev_b32_e32 v223, 16, v75
	v_and_b32_e32 v75, 0xffff0000, v75
	v_add_f32_e32 v223, v223, v194
	v_add_f32_e32 v75, v75, v195
	v_cvt_pk_bf16_f32 v75, v223, v75
	global_store_dwordx2 v222, v[74:75], s[2:3] offset:80
	v_lshlrev_b32_e32 v223, 16, v76
	v_and_b32_e32 v76, 0xffff0000, v76
	v_add_f32_e32 v223, v223, v196
	v_add_f32_e32 v76, v76, v197
	v_cvt_pk_bf16_f32 v76, v223, v76
	v_lshlrev_b32_e32 v223, 16, v77
	v_and_b32_e32 v77, 0xffff0000, v77
	v_add_f32_e32 v223, v223, v198
	v_add_f32_e32 v77, v77, v199
	v_cvt_pk_bf16_f32 v77, v223, v77
	global_store_dwordx2 v222, v[76:77], s[2:3] offset:96
	v_lshlrev_b32_e32 v223, 16, v78
	v_and_b32_e32 v78, 0xffff0000, v78
	v_add_f32_e32 v223, v223, v200
	v_add_f32_e32 v78, v78, v201
	v_cvt_pk_bf16_f32 v78, v223, v78
	v_lshlrev_b32_e32 v223, 16, v79
	v_and_b32_e32 v79, 0xffff0000, v79
	v_add_f32_e32 v223, v223, v202
	v_add_f32_e32 v79, v79, v203
	v_cvt_pk_bf16_f32 v79, v223, v79
	global_store_dwordx2 v222, v[78:79], s[2:3] offset:112
	s_mov_b64 s[0:1], 0x80000
	s_getreg_b32 s6, hwreg(HW_REG_XCC_ID, 0, 4)
	s_waitcnt vmcnt(0)
	s_barrier
	s_getreg_b32 s2, hwreg(HW_REG_HW_ID, 0, 6)
	s_and_b32 s2, s2, 63
	s_lshl_b32 s2, s2, 2
	s_add_i32 s2, s2, 0
	s_add_i32 s2, s2, 0x22ef0
	v_mov_b32_e32 v0, s2
	ds_read_b32 v0, v0
	s_waitcnt lgkmcnt(0)
	v_readfirstlane_b32 s2, v0
	v_mov_b32_e32 v0, v177
	s_nop 0
	v_mbcnt_lo_u32_b32 v0, -1, v0
	v_mbcnt_hi_u32_b32 v0, -1, v0
	v_lshl_add_u32 v0, s2, 6, v0
	s_nop 0
	v_cmp_eq_u32_e32 vcc, 0, v0
	s_and_saveexec_b64 s[2:3], vcc
	s_cbranch_execz .LBB0_798
	v_readlane_b32 s4, v254, 37
	s_waitcnt vmcnt(0) expcnt(0) lgkmcnt(0)
	s_nop 0
	v_mov_b32_e32 v0, s4
	ds_read_b32 v2, v0
	s_add_u32 s4, s66, s0
	v_readlane_b32 s0, v254, 38
	s_addc_u32 s5, s67, s1
	s_and_b32 s18, s6, 15
	v_mov_b32_e32 v0, s0
	ds_read_b32 v0, v0
	s_waitcnt lgkmcnt(1)
	v_cmp_ne_u32_e32 vcc, 0, v2
	s_cbranch_vccnz .LBB0_762
	s_add_u32 s0, s4, 0x1000
	s_addc_u32 s1, s5, 0
	s_add_u32 s6, s4, 0x1100
	s_addc_u32 s7, s5, 0
	s_add_u32 s8, s4, 0x1200
	s_addc_u32 s9, s5, 0
	s_add_u32 s10, s4, 0x1300
	s_addc_u32 s11, s5, 0
	s_mov_b32 s19, 1
	s_branch .LBB0_750
